# S5: f32 4x4x1 MFMA input projection plus v_cvt_pk_bf16_f32 for the bf16 state stores (replaces bit-trick, same RNE)
# speedup vs baseline: 1.0141x; 1.0012x over previous
; #define LAS __attribute__((address_space(3)))
; __device__ __forceinline__ unsigned f2bf(float f) { unsigned u = __builtin_bit_cast(unsigned, f); return (u + 0x7fffu + ((u >> 16) & 1u)) >> 16; }
; __device__ __forceinline__ void s5_phase(LAS unsigned char* lds, const unsigned char* ws, const bf16_t* proj, const float* c_re, const float* c_im, const float* dskip, bf16_t* z,
;                                          int vcu, int G, int wave, int lane) {
;     ...
; #pragma unroll
;             for (int k = 0; k < 32; ++k) {
;                 f32x2 xa = (f32x2){0.f, 0.f}, xb = (f32x2){0.f, 0.f};
; #pragma unroll
;                 for (int q = 0; q < 4; ++q) { const f32x4 u4 = *(const LAS f32x4*)(Uc + k * 16 + 4 * q);
;                     xa = __builtin_elementwise_fma((f32x2){u4[0], u4[0]}, (f32x2){bbre[4 * q], bbim[4 * q]}, xa);
;                     xb = __builtin_elementwise_fma((f32x2){u4[1], u4[1]}, (f32x2){bbre[4 * q + 1], bbim[4 * q + 1]}, xb);
;                     xa = __builtin_elementwise_fma((f32x2){u4[2], u4[2]}, (f32x2){bbre[4 * q + 2], bbim[4 * q + 2]}, xa);
;                     xb = __builtin_elementwise_fma((f32x2){u4[3], u4[3]}, (f32x2){bbre[4 * q + 3], bbim[4 * q + 3]}, xb); }
;                 const f32x2 xx = xa + xb;
;                 const float nr = are * hre - aim * him + xx[0], ni = are * him + aim * hre + xx[1]; hre = nr; him = ni;
;                 Hc[k * 136 + n] = (bf16_t)f2bf(hre); Hc[k * 136 + 64 + n] = (bf16_t)f2bf(him);
.LBB0_386:
	s_or_b64 exec, exec, s[0:1]
	s_waitcnt vmcnt(19)
	v_mov_b32_e32 v40, s14
	v_and_b32_e32 v248, 3, v193
	v_lshl_add_u32 v248, v248, 6, v40
	s_waitcnt vmcnt(18)
	ds_read_b128 v[216:219], v248 offset:0
	ds_read_b128 v[220:223], v248 offset:16
	ds_read_b128 v[224:227], v248 offset:32
	ds_read_b128 v[228:231], v248 offset:48
	s_waitcnt lgkmcnt(0)
	v_mfma_f32_4x4x1_16b_f32 v[232:235], v216, v64, 0
	v_mfma_f32_4x4x1_16b_f32 v[236:239], v216, v65, 0
	v_mfma_f32_4x4x1_16b_f32 v[240:243], v217, v12, 0
	v_mfma_f32_4x4x1_16b_f32 v[244:247], v217, v13, 0
	v_mfma_f32_4x4x1_16b_f32 v[232:235], v218, v66, v[232:235]
	v_mfma_f32_4x4x1_16b_f32 v[236:239], v218, v67, v[236:239]
	v_mfma_f32_4x4x1_16b_f32 v[240:243], v219, v14, v[240:243]
	v_mfma_f32_4x4x1_16b_f32 v[244:247], v219, v15, v[244:247]
	v_mfma_f32_4x4x1_16b_f32 v[232:235], v220, v68, v[232:235]
	v_mfma_f32_4x4x1_16b_f32 v[236:239], v220, v69, v[236:239]
	v_mfma_f32_4x4x1_16b_f32 v[240:243], v221, v8, v[240:243]
	v_mfma_f32_4x4x1_16b_f32 v[244:247], v221, v9, v[244:247]
	v_mfma_f32_4x4x1_16b_f32 v[232:235], v222, v70, v[232:235]
	v_mfma_f32_4x4x1_16b_f32 v[236:239], v222, v71, v[236:239]
	v_mfma_f32_4x4x1_16b_f32 v[240:243], v223, v10, v[240:243]
	v_mfma_f32_4x4x1_16b_f32 v[244:247], v223, v11, v[244:247]
	v_mfma_f32_4x4x1_16b_f32 v[232:235], v224, v72, v[232:235]
	v_mfma_f32_4x4x1_16b_f32 v[236:239], v224, v73, v[236:239]
	v_mfma_f32_4x4x1_16b_f32 v[240:243], v225, v4, v[240:243]
	v_mfma_f32_4x4x1_16b_f32 v[244:247], v225, v5, v[244:247]
	v_mfma_f32_4x4x1_16b_f32 v[232:235], v226, v74, v[232:235]
	v_mfma_f32_4x4x1_16b_f32 v[236:239], v226, v75, v[236:239]
	v_mfma_f32_4x4x1_16b_f32 v[240:243], v227, v6, v[240:243]
	v_mfma_f32_4x4x1_16b_f32 v[244:247], v227, v7, v[244:247]
	v_mfma_f32_4x4x1_16b_f32 v[232:235], v228, v76, v[232:235]
	v_mfma_f32_4x4x1_16b_f32 v[236:239], v228, v77, v[236:239]
	v_mfma_f32_4x4x1_16b_f32 v[240:243], v229, v0, v[240:243]
	v_mfma_f32_4x4x1_16b_f32 v[244:247], v229, v1, v[244:247]
	v_mfma_f32_4x4x1_16b_f32 v[232:235], v230, v78, v[232:235]
	v_mfma_f32_4x4x1_16b_f32 v[236:239], v230, v79, v[236:239]
	v_mfma_f32_4x4x1_16b_f32 v[240:243], v231, v2, v[240:243]
	v_mfma_f32_4x4x1_16b_f32 v[244:247], v231, v3, v[244:247]
	s_nop 4
	s_waitcnt vmcnt(13)
	v_lshlrev_b32_e32 v108, 16, v108
	v_add_f32_e32 v42, v240, v232
	v_add_f32_e32 v43, v244, v236
	v_mul_f32_e32 v44, v61, v87
	v_pk_fma_f32 v[44:45], v[60:61], v[86:87], v[44:45] op_sel_hi:[1,1,0] neg_lo:[0,0,1] neg_hi:[0,0,1]
	s_nop 0
	v_pk_add_f32 v[46:47], v[44:45], v[42:43]
	v_mov_b32_e32 v44, v87
	v_pk_mul_f32 v[44:45], v[60:61], v[44:45]
	v_pk_fma_f32 v[44:45], v[50:51], v[86:87], v[44:45]
	v_pk_add_f32 v[86:87], v[44:45], v[42:43] op_sel:[0,1] op_sel_hi:[1,0]
	v_cvt_pk_bf16_f32 v41, v46, v86
	ds_write_b16 v88, v41
	ds_write_b16_d16_hi v88, v41 offset:128
	v_add_f32_e32 v42, v241, v233
	v_add_f32_e32 v43, v245, v237
	v_pk_mul_f32 v[44:45], v[50:51], v[86:87]
	s_nop 0
	v_pk_fma_f32 v[44:45], v[60:61], v[46:47], v[44:45] neg_lo:[0,0,1] neg_hi:[0,0,1]
	s_nop 0
	v_pk_add_f32 v[134:135], v[44:45], v[42:43]
	v_pk_mul_f32 v[44:45], v[50:51], v[46:47]
	v_pk_fma_f32 v[44:45], v[60:61], v[86:87], v[44:45]
	v_pk_add_f32 v[46:47], v[44:45], v[42:43] op_sel:[0,1] op_sel_hi:[1,0]
	v_cvt_pk_bf16_f32 v41, v134, v46
	ds_write_b16 v88, v41 offset:272
	ds_write_b16_d16_hi v88, v41 offset:400
	v_add_f32_e32 v42, v242, v234
	v_add_f32_e32 v43, v246, v238
	v_pk_mul_f32 v[44:45], v[50:51], v[46:47]
	s_nop 0
	v_pk_fma_f32 v[44:45], v[60:61], v[134:135], v[44:45] neg_lo:[0,0,1] neg_hi:[0,0,1]
	s_nop 0
	v_pk_add_f32 v[86:87], v[44:45], v[42:43]
	v_pk_mul_f32 v[44:45], v[50:51], v[134:135]
	v_pk_fma_f32 v[44:45], v[60:61], v[46:47], v[44:45]
	v_pk_add_f32 v[46:47], v[44:45], v[42:43] op_sel:[0,1] op_sel_hi:[1,0]
	v_cvt_pk_bf16_f32 v41, v86, v46
	ds_write_b16 v88, v41 offset:544
	ds_write_b16_d16_hi v88, v41 offset:672
	v_add_f32_e32 v42, v243, v235
	v_add_f32_e32 v43, v247, v239
	v_pk_mul_f32 v[44:45], v[50:51], v[46:47]
	s_nop 0
	v_pk_fma_f32 v[44:45], v[60:61], v[86:87], v[44:45] neg_lo:[0,0,1] neg_hi:[0,0,1]
	s_nop 0
	v_pk_add_f32 v[134:135], v[44:45], v[42:43]
	v_pk_mul_f32 v[44:45], v[50:51], v[86:87]
	v_pk_fma_f32 v[44:45], v[60:61], v[46:47], v[44:45]
	v_pk_add_f32 v[46:47], v[44:45], v[42:43] op_sel:[0,1] op_sel_hi:[1,0]
	v_cvt_pk_bf16_f32 v41, v134, v46
	ds_write_b16 v88, v41 offset:816
	ds_write_b16_d16_hi v88, v41 offset:944
	ds_read_b128 v[216:219], v248 offset:256
	ds_read_b128 v[220:223], v248 offset:272
	ds_read_b128 v[224:227], v248 offset:288
	ds_read_b128 v[228:231], v248 offset:304
	s_waitcnt lgkmcnt(0)
; #define LAS __attribute__((address_space(3)))
; __device__ __forceinline__ unsigned f2bf(float f) { unsigned u = __builtin_bit_cast(unsigned, f); return (u + 0x7fffu + ((u >> 16) & 1u)) >> 16; }
; __device__ __forceinline__ void s5_phase(LAS unsigned char* lds, const unsigned char* ws, const bf16_t* proj, const float* c_re, const float* c_im, const float* dskip, bf16_t* z,
;                                          int vcu, int G, int wave, int lane) {
;     ...
;             for (int k = 0; k < 32; ++k) {
;                 f32x2 xa = (f32x2){0.f, 0.f}, xb = (f32x2){0.f, 0.f};
; #pragma unroll
;                 for (int q = 0; q < 4; ++q) { const f32x4 u4 = *(const LAS f32x4*)(Uc + k * 16 + 4 * q);
;                     xa = __builtin_elementwise_fma((f32x2){u4[0], u4[0]}, (f32x2){bbre[4 * q], bbim[4 * q]}, xa);
;                     xb = __builtin_elementwise_fma((f32x2){u4[1], u4[1]}, (f32x2){bbre[4 * q + 1], bbim[4 * q + 1]}, xb);
;                     xa = __builtin_elementwise_fma((f32x2){u4[2], u4[2]}, (f32x2){bbre[4 * q + 2], bbim[4 * q + 2]}, xa);
;                     xb = __builtin_elementwise_fma((f32x2){u4[3], u4[3]}, (f32x2){bbre[4 * q + 3], bbim[4 * q + 3]}, xb); }
;                 const f32x2 xx = xa + xb;
;                 const float nr = are * hre - aim * him + xx[0], ni = are * him + aim * hre + xx[1]; hre = nr; him = ni;
;                 Hc[k * 136 + n] = (bf16_t)f2bf(hre); Hc[k * 136 + 64 + n] = (bf16_t)f2bf(him);
	v_mfma_f32_4x4x1_16b_f32 v[232:235], v216, v64, 0
	v_mfma_f32_4x4x1_16b_f32 v[236:239], v216, v65, 0
	v_mfma_f32_4x4x1_16b_f32 v[240:243], v217, v12, 0
	v_mfma_f32_4x4x1_16b_f32 v[244:247], v217, v13, 0
	v_mfma_f32_4x4x1_16b_f32 v[232:235], v218, v66, v[232:235]
	v_mfma_f32_4x4x1_16b_f32 v[236:239], v218, v67, v[236:239]
	v_mfma_f32_4x4x1_16b_f32 v[240:243], v219, v14, v[240:243]
	v_mfma_f32_4x4x1_16b_f32 v[244:247], v219, v15, v[244:247]
	v_mfma_f32_4x4x1_16b_f32 v[232:235], v220, v68, v[232:235]
	v_mfma_f32_4x4x1_16b_f32 v[236:239], v220, v69, v[236:239]
	v_mfma_f32_4x4x1_16b_f32 v[240:243], v221, v8, v[240:243]
	v_mfma_f32_4x4x1_16b_f32 v[244:247], v221, v9, v[244:247]
	v_mfma_f32_4x4x1_16b_f32 v[232:235], v222, v70, v[232:235]
	v_mfma_f32_4x4x1_16b_f32 v[236:239], v222, v71, v[236:239]
	v_mfma_f32_4x4x1_16b_f32 v[240:243], v223, v10, v[240:243]
	v_mfma_f32_4x4x1_16b_f32 v[244:247], v223, v11, v[244:247]
	v_mfma_f32_4x4x1_16b_f32 v[232:235], v224, v72, v[232:235]
	v_mfma_f32_4x4x1_16b_f32 v[236:239], v224, v73, v[236:239]
	v_mfma_f32_4x4x1_16b_f32 v[240:243], v225, v4, v[240:243]
	v_mfma_f32_4x4x1_16b_f32 v[244:247], v225, v5, v[244:247]
	v_mfma_f32_4x4x1_16b_f32 v[232:235], v226, v74, v[232:235]
	v_mfma_f32_4x4x1_16b_f32 v[236:239], v226, v75, v[236:239]
	v_mfma_f32_4x4x1_16b_f32 v[240:243], v227, v6, v[240:243]
	v_mfma_f32_4x4x1_16b_f32 v[244:247], v227, v7, v[244:247]
	v_mfma_f32_4x4x1_16b_f32 v[232:235], v228, v76, v[232:235]
	v_mfma_f32_4x4x1_16b_f32 v[236:239], v228, v77, v[236:239]
	v_mfma_f32_4x4x1_16b_f32 v[240:243], v229, v0, v[240:243]
	v_mfma_f32_4x4x1_16b_f32 v[244:247], v229, v1, v[244:247]
	v_mfma_f32_4x4x1_16b_f32 v[232:235], v230, v78, v[232:235]
	v_mfma_f32_4x4x1_16b_f32 v[236:239], v230, v79, v[236:239]
	v_mfma_f32_4x4x1_16b_f32 v[240:243], v231, v2, v[240:243]
	v_mfma_f32_4x4x1_16b_f32 v[244:247], v231, v3, v[244:247]
	s_nop 4
	v_add_f32_e32 v42, v240, v232
	v_add_f32_e32 v43, v244, v236
	v_pk_mul_f32 v[44:45], v[50:51], v[46:47]
	s_nop 0
	v_pk_fma_f32 v[44:45], v[60:61], v[134:135], v[44:45] neg_lo:[0,0,1] neg_hi:[0,0,1]
	s_nop 0
	v_pk_add_f32 v[86:87], v[44:45], v[42:43]
	v_pk_mul_f32 v[44:45], v[50:51], v[134:135]
	v_pk_fma_f32 v[44:45], v[60:61], v[46:47], v[44:45]
	v_pk_add_f32 v[46:47], v[44:45], v[42:43] op_sel:[0,1] op_sel_hi:[1,0]
	v_cvt_pk_bf16_f32 v41, v86, v46
	ds_write_b16 v88, v41 offset:1088
	ds_write_b16_d16_hi v88, v41 offset:1216
	v_add_f32_e32 v42, v241, v233
	v_add_f32_e32 v43, v245, v237
	v_pk_mul_f32 v[44:45], v[50:51], v[46:47]
	s_nop 0
	v_pk_fma_f32 v[44:45], v[60:61], v[86:87], v[44:45] neg_lo:[0,0,1] neg_hi:[0,0,1]
	s_nop 0
	v_pk_add_f32 v[134:135], v[44:45], v[42:43]
	v_pk_mul_f32 v[44:45], v[50:51], v[86:87]
	v_pk_fma_f32 v[44:45], v[60:61], v[46:47], v[44:45]
	v_pk_add_f32 v[46:47], v[44:45], v[42:43] op_sel:[0,1] op_sel_hi:[1,0]
	v_cvt_pk_bf16_f32 v41, v134, v46
	ds_write_b16 v88, v41 offset:1360
	ds_write_b16_d16_hi v88, v41 offset:1488
	v_add_f32_e32 v42, v242, v234
	v_add_f32_e32 v43, v246, v238
	v_pk_mul_f32 v[44:45], v[50:51], v[46:47]
	s_nop 0
	v_pk_fma_f32 v[44:45], v[60:61], v[134:135], v[44:45] neg_lo:[0,0,1] neg_hi:[0,0,1]
	s_nop 0
	v_pk_add_f32 v[86:87], v[44:45], v[42:43]
	v_pk_mul_f32 v[44:45], v[50:51], v[134:135]
	v_pk_fma_f32 v[44:45], v[60:61], v[46:47], v[44:45]
	v_pk_add_f32 v[46:47], v[44:45], v[42:43] op_sel:[0,1] op_sel_hi:[1,0]
	v_cvt_pk_bf16_f32 v41, v86, v46
	ds_write_b16 v88, v41 offset:1632
	ds_write_b16_d16_hi v88, v41 offset:1760
	v_add_f32_e32 v42, v243, v235
	v_add_f32_e32 v43, v247, v239
	v_pk_mul_f32 v[44:45], v[50:51], v[46:47]
	s_nop 0
	v_pk_fma_f32 v[44:45], v[60:61], v[86:87], v[44:45] neg_lo:[0,0,1] neg_hi:[0,0,1]
	s_nop 0
	v_pk_add_f32 v[134:135], v[44:45], v[42:43]
	v_pk_mul_f32 v[44:45], v[50:51], v[86:87]
	v_pk_fma_f32 v[44:45], v[60:61], v[46:47], v[44:45]
	v_pk_add_f32 v[46:47], v[44:45], v[42:43] op_sel:[0,1] op_sel_hi:[1,0]
	v_cvt_pk_bf16_f32 v41, v134, v46
	ds_write_b16 v88, v41 offset:1904
	ds_write_b16_d16_hi v88, v41 offset:2032
	ds_read_b128 v[216:219], v248 offset:512
	ds_read_b128 v[220:223], v248 offset:528
	ds_read_b128 v[224:227], v248 offset:544
	ds_read_b128 v[228:231], v248 offset:560
	s_waitcnt lgkmcnt(0)
	v_mfma_f32_4x4x1_16b_f32 v[232:235], v216, v64, 0
	v_mfma_f32_4x4x1_16b_f32 v[236:239], v216, v65, 0
	v_mfma_f32_4x4x1_16b_f32 v[240:243], v217, v12, 0
	v_mfma_f32_4x4x1_16b_f32 v[244:247], v217, v13, 0
	v_mfma_f32_4x4x1_16b_f32 v[232:235], v218, v66, v[232:235]
	v_mfma_f32_4x4x1_16b_f32 v[236:239], v218, v67, v[236:239]
	v_mfma_f32_4x4x1_16b_f32 v[240:243], v219, v14, v[240:243]
	v_mfma_f32_4x4x1_16b_f32 v[244:247], v219, v15, v[244:247]
	v_mfma_f32_4x4x1_16b_f32 v[232:235], v220, v68, v[232:235]
	v_mfma_f32_4x4x1_16b_f32 v[236:239], v220, v69, v[236:239]
	v_mfma_f32_4x4x1_16b_f32 v[240:243], v221, v8, v[240:243]
	v_mfma_f32_4x4x1_16b_f32 v[244:247], v221, v9, v[244:247]
	v_mfma_f32_4x4x1_16b_f32 v[232:235], v222, v70, v[232:235]
	v_mfma_f32_4x4x1_16b_f32 v[236:239], v222, v71, v[236:239]
	v_mfma_f32_4x4x1_16b_f32 v[240:243], v223, v10, v[240:243]
	v_mfma_f32_4x4x1_16b_f32 v[244:247], v223, v11, v[244:247]
	v_mfma_f32_4x4x1_16b_f32 v[232:235], v224, v72, v[232:235]
	v_mfma_f32_4x4x1_16b_f32 v[236:239], v224, v73, v[236:239]
	v_mfma_f32_4x4x1_16b_f32 v[240:243], v225, v4, v[240:243]
	v_mfma_f32_4x4x1_16b_f32 v[244:247], v225, v5, v[244:247]
	v_mfma_f32_4x4x1_16b_f32 v[232:235], v226, v74, v[232:235]
	v_mfma_f32_4x4x1_16b_f32 v[236:239], v226, v75, v[236:239]
	v_mfma_f32_4x4x1_16b_f32 v[240:243], v227, v6, v[240:243]
	v_mfma_f32_4x4x1_16b_f32 v[244:247], v227, v7, v[244:247]
	v_mfma_f32_4x4x1_16b_f32 v[232:235], v228, v76, v[232:235]
; #define LAS __attribute__((address_space(3)))
; __device__ __forceinline__ unsigned f2bf(float f) { unsigned u = __builtin_bit_cast(unsigned, f); return (u + 0x7fffu + ((u >> 16) & 1u)) >> 16; }
; __device__ __forceinline__ void s5_phase(LAS unsigned char* lds, const unsigned char* ws, const bf16_t* proj, const float* c_re, const float* c_im, const float* dskip, bf16_t* z,
;                                          int vcu, int G, int wave, int lane) {
;     ...
;             for (int k = 0; k < 32; ++k) {
;                 f32x2 xa = (f32x2){0.f, 0.f}, xb = (f32x2){0.f, 0.f};
; #pragma unroll
;                 for (int q = 0; q < 4; ++q) { const f32x4 u4 = *(const LAS f32x4*)(Uc + k * 16 + 4 * q);
;                     xa = __builtin_elementwise_fma((f32x2){u4[0], u4[0]}, (f32x2){bbre[4 * q], bbim[4 * q]}, xa);
;                     xb = __builtin_elementwise_fma((f32x2){u4[1], u4[1]}, (f32x2){bbre[4 * q + 1], bbim[4 * q + 1]}, xb);
;                     xa = __builtin_elementwise_fma((f32x2){u4[2], u4[2]}, (f32x2){bbre[4 * q + 2], bbim[4 * q + 2]}, xa);
;                     xb = __builtin_elementwise_fma((f32x2){u4[3], u4[3]}, (f32x2){bbre[4 * q + 3], bbim[4 * q + 3]}, xb); }
;                 const f32x2 xx = xa + xb;
;                 const float nr = are * hre - aim * him + xx[0], ni = are * him + aim * hre + xx[1]; hre = nr; him = ni;
;                 Hc[k * 136 + n] = (bf16_t)f2bf(hre); Hc[k * 136 + 64 + n] = (bf16_t)f2bf(him);
	v_mfma_f32_4x4x1_16b_f32 v[236:239], v228, v77, v[236:239]
	v_mfma_f32_4x4x1_16b_f32 v[240:243], v229, v0, v[240:243]
	v_mfma_f32_4x4x1_16b_f32 v[244:247], v229, v1, v[244:247]
	v_mfma_f32_4x4x1_16b_f32 v[232:235], v230, v78, v[232:235]
	v_mfma_f32_4x4x1_16b_f32 v[236:239], v230, v79, v[236:239]
	v_mfma_f32_4x4x1_16b_f32 v[240:243], v231, v2, v[240:243]
	v_mfma_f32_4x4x1_16b_f32 v[244:247], v231, v3, v[244:247]
	s_nop 4
	v_add_f32_e32 v42, v240, v232
	v_add_f32_e32 v43, v244, v236
	v_pk_mul_f32 v[44:45], v[50:51], v[46:47]
	s_nop 0
	v_pk_fma_f32 v[44:45], v[60:61], v[134:135], v[44:45] neg_lo:[0,0,1] neg_hi:[0,0,1]
	s_nop 0
	v_pk_add_f32 v[86:87], v[44:45], v[42:43]
	v_pk_mul_f32 v[44:45], v[50:51], v[134:135]
	v_pk_fma_f32 v[44:45], v[60:61], v[46:47], v[44:45]
	v_pk_add_f32 v[46:47], v[44:45], v[42:43] op_sel:[0,1] op_sel_hi:[1,0]
	v_cvt_pk_bf16_f32 v41, v86, v46
	ds_write_b16 v88, v41 offset:2176
	ds_write_b16_d16_hi v88, v41 offset:2304
	v_add_f32_e32 v42, v241, v233
	v_add_f32_e32 v43, v245, v237
	v_pk_mul_f32 v[44:45], v[50:51], v[46:47]
	s_nop 0
	v_pk_fma_f32 v[44:45], v[60:61], v[86:87], v[44:45] neg_lo:[0,0,1] neg_hi:[0,0,1]
	s_nop 0
	v_pk_add_f32 v[134:135], v[44:45], v[42:43]
	v_pk_mul_f32 v[44:45], v[50:51], v[86:87]
	v_pk_fma_f32 v[44:45], v[60:61], v[46:47], v[44:45]
	v_pk_add_f32 v[46:47], v[44:45], v[42:43] op_sel:[0,1] op_sel_hi:[1,0]
	v_cvt_pk_bf16_f32 v41, v134, v46
	ds_write_b16 v88, v41 offset:2448
	ds_write_b16_d16_hi v88, v41 offset:2576
	v_add_f32_e32 v42, v242, v234
	v_add_f32_e32 v43, v246, v238
	v_pk_mul_f32 v[44:45], v[50:51], v[46:47]
	s_nop 0
	v_pk_fma_f32 v[44:45], v[60:61], v[134:135], v[44:45] neg_lo:[0,0,1] neg_hi:[0,0,1]
	s_nop 0
	v_pk_add_f32 v[86:87], v[44:45], v[42:43]
	v_pk_mul_f32 v[44:45], v[50:51], v[134:135]
	v_pk_fma_f32 v[44:45], v[60:61], v[46:47], v[44:45]
	v_pk_add_f32 v[46:47], v[44:45], v[42:43] op_sel:[0,1] op_sel_hi:[1,0]
	v_cvt_pk_bf16_f32 v41, v86, v46
	ds_write_b16 v88, v41 offset:2720
	ds_write_b16_d16_hi v88, v41 offset:2848
	v_add_f32_e32 v42, v243, v235
	v_add_f32_e32 v43, v247, v239
	v_pk_mul_f32 v[44:45], v[50:51], v[46:47]
	s_nop 0
	v_pk_fma_f32 v[44:45], v[60:61], v[86:87], v[44:45] neg_lo:[0,0,1] neg_hi:[0,0,1]
	s_nop 0
	v_pk_add_f32 v[134:135], v[44:45], v[42:43]
	v_pk_mul_f32 v[44:45], v[50:51], v[86:87]
	v_pk_fma_f32 v[44:45], v[60:61], v[46:47], v[44:45]
	v_pk_add_f32 v[46:47], v[44:45], v[42:43] op_sel:[0,1] op_sel_hi:[1,0]
	v_cvt_pk_bf16_f32 v41, v134, v46
	ds_write_b16 v88, v41 offset:2992
	ds_write_b16_d16_hi v88, v41 offset:3120
	ds_read_b128 v[216:219], v248 offset:768
	ds_read_b128 v[220:223], v248 offset:784
	ds_read_b128 v[224:227], v248 offset:800
	ds_read_b128 v[228:231], v248 offset:816
	s_waitcnt lgkmcnt(0)
	v_mfma_f32_4x4x1_16b_f32 v[232:235], v216, v64, 0
	v_mfma_f32_4x4x1_16b_f32 v[236:239], v216, v65, 0
	v_mfma_f32_4x4x1_16b_f32 v[240:243], v217, v12, 0
	v_mfma_f32_4x4x1_16b_f32 v[244:247], v217, v13, 0
	v_mfma_f32_4x4x1_16b_f32 v[232:235], v218, v66, v[232:235]
	v_mfma_f32_4x4x1_16b_f32 v[236:239], v218, v67, v[236:239]
	v_mfma_f32_4x4x1_16b_f32 v[240:243], v219, v14, v[240:243]
	v_mfma_f32_4x4x1_16b_f32 v[244:247], v219, v15, v[244:247]
	v_mfma_f32_4x4x1_16b_f32 v[232:235], v220, v68, v[232:235]
	v_mfma_f32_4x4x1_16b_f32 v[236:239], v220, v69, v[236:239]
	v_mfma_f32_4x4x1_16b_f32 v[240:243], v221, v8, v[240:243]
	v_mfma_f32_4x4x1_16b_f32 v[244:247], v221, v9, v[244:247]
	v_mfma_f32_4x4x1_16b_f32 v[232:235], v222, v70, v[232:235]
	v_mfma_f32_4x4x1_16b_f32 v[236:239], v222, v71, v[236:239]
	v_mfma_f32_4x4x1_16b_f32 v[240:243], v223, v10, v[240:243]
	v_mfma_f32_4x4x1_16b_f32 v[244:247], v223, v11, v[244:247]
	v_mfma_f32_4x4x1_16b_f32 v[232:235], v224, v72, v[232:235]
	v_mfma_f32_4x4x1_16b_f32 v[236:239], v224, v73, v[236:239]
	v_mfma_f32_4x4x1_16b_f32 v[240:243], v225, v4, v[240:243]
	v_mfma_f32_4x4x1_16b_f32 v[244:247], v225, v5, v[244:247]
	v_mfma_f32_4x4x1_16b_f32 v[232:235], v226, v74, v[232:235]
	v_mfma_f32_4x4x1_16b_f32 v[236:239], v226, v75, v[236:239]
	v_mfma_f32_4x4x1_16b_f32 v[240:243], v227, v6, v[240:243]
	v_mfma_f32_4x4x1_16b_f32 v[244:247], v227, v7, v[244:247]
	v_mfma_f32_4x4x1_16b_f32 v[232:235], v228, v76, v[232:235]
	v_mfma_f32_4x4x1_16b_f32 v[236:239], v228, v77, v[236:239]
	v_mfma_f32_4x4x1_16b_f32 v[240:243], v229, v0, v[240:243]
	v_mfma_f32_4x4x1_16b_f32 v[244:247], v229, v1, v[244:247]
	v_mfma_f32_4x4x1_16b_f32 v[232:235], v230, v78, v[232:235]
	v_mfma_f32_4x4x1_16b_f32 v[236:239], v230, v79, v[236:239]
	v_mfma_f32_4x4x1_16b_f32 v[240:243], v231, v2, v[240:243]
	v_mfma_f32_4x4x1_16b_f32 v[244:247], v231, v3, v[244:247]
	s_nop 4
	v_add_f32_e32 v42, v240, v232
	v_add_f32_e32 v43, v244, v236
	v_pk_mul_f32 v[44:45], v[50:51], v[46:47]
	s_nop 0
	v_pk_fma_f32 v[44:45], v[60:61], v[134:135], v[44:45] neg_lo:[0,0,1] neg_hi:[0,0,1]
	s_nop 0
	v_pk_add_f32 v[86:87], v[44:45], v[42:43]
	v_pk_mul_f32 v[44:45], v[50:51], v[134:135]
	v_pk_fma_f32 v[44:45], v[60:61], v[46:47], v[44:45]
	v_pk_add_f32 v[46:47], v[44:45], v[42:43] op_sel:[0,1] op_sel_hi:[1,0]
	v_cvt_pk_bf16_f32 v41, v86, v46
	ds_write_b16 v88, v41 offset:3264
	ds_write_b16_d16_hi v88, v41 offset:3392
	v_add_f32_e32 v42, v241, v233
	v_add_f32_e32 v43, v245, v237
	v_pk_mul_f32 v[44:45], v[50:51], v[46:47]
	s_nop 0
	v_pk_fma_f32 v[44:45], v[60:61], v[86:87], v[44:45] neg_lo:[0,0,1] neg_hi:[0,0,1]
	s_nop 0
	v_pk_add_f32 v[134:135], v[44:45], v[42:43]
	v_pk_mul_f32 v[44:45], v[50:51], v[86:87]
	v_pk_fma_f32 v[44:45], v[60:61], v[46:47], v[44:45]
	v_pk_add_f32 v[46:47], v[44:45], v[42:43] op_sel:[0,1] op_sel_hi:[1,0]
	v_cvt_pk_bf16_f32 v41, v134, v46
	ds_write_b16 v88, v41 offset:3536
	ds_write_b16_d16_hi v88, v41 offset:3664
	v_add_f32_e32 v42, v242, v234
	v_add_f32_e32 v43, v246, v238
	v_pk_mul_f32 v[44:45], v[50:51], v[46:47]
	s_nop 0
	v_pk_fma_f32 v[44:45], v[60:61], v[134:135], v[44:45] neg_lo:[0,0,1] neg_hi:[0,0,1]
	s_nop 0
	v_pk_add_f32 v[86:87], v[44:45], v[42:43]
	v_pk_mul_f32 v[44:45], v[50:51], v[134:135]
	v_pk_fma_f32 v[44:45], v[60:61], v[46:47], v[44:45]
	v_pk_add_f32 v[46:47], v[44:45], v[42:43] op_sel:[0,1] op_sel_hi:[1,0]
	v_cvt_pk_bf16_f32 v41, v86, v46
	ds_write_b16 v88, v41 offset:3808
	ds_write_b16_d16_hi v88, v41 offset:3936
	v_add_f32_e32 v42, v243, v235
	v_add_f32_e32 v43, v247, v239
	v_pk_mul_f32 v[44:45], v[50:51], v[46:47]
	s_nop 0
	v_pk_fma_f32 v[44:45], v[60:61], v[86:87], v[44:45] neg_lo:[0,0,1] neg_hi:[0,0,1]
	s_nop 0
	v_pk_add_f32 v[134:135], v[44:45], v[42:43]
	v_pk_mul_f32 v[44:45], v[50:51], v[86:87]
	v_pk_fma_f32 v[44:45], v[60:61], v[46:47], v[44:45]
	v_pk_add_f32 v[46:47], v[44:45], v[42:43] op_sel:[0,1] op_sel_hi:[1,0]
	v_cvt_pk_bf16_f32 v41, v134, v46
	ds_write_b16 v88, v41 offset:4080
	ds_write_b16_d16_hi v88, v41 offset:4208
	ds_read_b128 v[216:219], v248 offset:1024
	ds_read_b128 v[220:223], v248 offset:1040
	ds_read_b128 v[224:227], v248 offset:1056
	ds_read_b128 v[228:231], v248 offset:1072
	s_waitcnt lgkmcnt(0)
; #define LAS __attribute__((address_space(3)))
; __device__ __forceinline__ unsigned f2bf(float f) { unsigned u = __builtin_bit_cast(unsigned, f); return (u + 0x7fffu + ((u >> 16) & 1u)) >> 16; }
; __device__ __forceinline__ void s5_phase(LAS unsigned char* lds, const unsigned char* ws, const bf16_t* proj, const float* c_re, const float* c_im, const float* dskip, bf16_t* z,
;                                          int vcu, int G, int wave, int lane) {
;     ...
;             for (int k = 0; k < 32; ++k) {
;                 f32x2 xa = (f32x2){0.f, 0.f}, xb = (f32x2){0.f, 0.f};
; #pragma unroll
;                 for (int q = 0; q < 4; ++q) { const f32x4 u4 = *(const LAS f32x4*)(Uc + k * 16 + 4 * q);
;                     xa = __builtin_elementwise_fma((f32x2){u4[0], u4[0]}, (f32x2){bbre[4 * q], bbim[4 * q]}, xa);
;                     xb = __builtin_elementwise_fma((f32x2){u4[1], u4[1]}, (f32x2){bbre[4 * q + 1], bbim[4 * q + 1]}, xb);
;                     xa = __builtin_elementwise_fma((f32x2){u4[2], u4[2]}, (f32x2){bbre[4 * q + 2], bbim[4 * q + 2]}, xa);
;                     xb = __builtin_elementwise_fma((f32x2){u4[3], u4[3]}, (f32x2){bbre[4 * q + 3], bbim[4 * q + 3]}, xb); }
;                 const f32x2 xx = xa + xb;
;                 const float nr = are * hre - aim * him + xx[0], ni = are * him + aim * hre + xx[1]; hre = nr; him = ni;
;                 Hc[k * 136 + n] = (bf16_t)f2bf(hre); Hc[k * 136 + 64 + n] = (bf16_t)f2bf(him);
	v_mfma_f32_4x4x1_16b_f32 v[232:235], v216, v64, 0
	v_mfma_f32_4x4x1_16b_f32 v[236:239], v216, v65, 0
	v_mfma_f32_4x4x1_16b_f32 v[240:243], v217, v12, 0
	v_mfma_f32_4x4x1_16b_f32 v[244:247], v217, v13, 0
	v_mfma_f32_4x4x1_16b_f32 v[232:235], v218, v66, v[232:235]
	v_mfma_f32_4x4x1_16b_f32 v[236:239], v218, v67, v[236:239]
	v_mfma_f32_4x4x1_16b_f32 v[240:243], v219, v14, v[240:243]
	v_mfma_f32_4x4x1_16b_f32 v[244:247], v219, v15, v[244:247]
	v_mfma_f32_4x4x1_16b_f32 v[232:235], v220, v68, v[232:235]
	v_mfma_f32_4x4x1_16b_f32 v[236:239], v220, v69, v[236:239]
	v_mfma_f32_4x4x1_16b_f32 v[240:243], v221, v8, v[240:243]
	v_mfma_f32_4x4x1_16b_f32 v[244:247], v221, v9, v[244:247]
	v_mfma_f32_4x4x1_16b_f32 v[232:235], v222, v70, v[232:235]
	v_mfma_f32_4x4x1_16b_f32 v[236:239], v222, v71, v[236:239]
	v_mfma_f32_4x4x1_16b_f32 v[240:243], v223, v10, v[240:243]
	v_mfma_f32_4x4x1_16b_f32 v[244:247], v223, v11, v[244:247]
	v_mfma_f32_4x4x1_16b_f32 v[232:235], v224, v72, v[232:235]
	v_mfma_f32_4x4x1_16b_f32 v[236:239], v224, v73, v[236:239]
	v_mfma_f32_4x4x1_16b_f32 v[240:243], v225, v4, v[240:243]
	v_mfma_f32_4x4x1_16b_f32 v[244:247], v225, v5, v[244:247]
	v_mfma_f32_4x4x1_16b_f32 v[232:235], v226, v74, v[232:235]
	v_mfma_f32_4x4x1_16b_f32 v[236:239], v226, v75, v[236:239]
	v_mfma_f32_4x4x1_16b_f32 v[240:243], v227, v6, v[240:243]
	v_mfma_f32_4x4x1_16b_f32 v[244:247], v227, v7, v[244:247]
	v_mfma_f32_4x4x1_16b_f32 v[232:235], v228, v76, v[232:235]
	v_mfma_f32_4x4x1_16b_f32 v[236:239], v228, v77, v[236:239]
	v_mfma_f32_4x4x1_16b_f32 v[240:243], v229, v0, v[240:243]
	v_mfma_f32_4x4x1_16b_f32 v[244:247], v229, v1, v[244:247]
	v_mfma_f32_4x4x1_16b_f32 v[232:235], v230, v78, v[232:235]
	v_mfma_f32_4x4x1_16b_f32 v[236:239], v230, v79, v[236:239]
	v_mfma_f32_4x4x1_16b_f32 v[240:243], v231, v2, v[240:243]
	v_mfma_f32_4x4x1_16b_f32 v[244:247], v231, v3, v[244:247]
	s_nop 4
	v_add_f32_e32 v42, v240, v232
	v_add_f32_e32 v43, v244, v236
	v_pk_mul_f32 v[44:45], v[50:51], v[46:47]
	s_nop 0
	v_pk_fma_f32 v[44:45], v[60:61], v[134:135], v[44:45] neg_lo:[0,0,1] neg_hi:[0,0,1]
	s_nop 0
	v_pk_add_f32 v[86:87], v[44:45], v[42:43]
	v_pk_mul_f32 v[44:45], v[50:51], v[134:135]
	v_pk_fma_f32 v[44:45], v[60:61], v[46:47], v[44:45]
	v_pk_add_f32 v[46:47], v[44:45], v[42:43] op_sel:[0,1] op_sel_hi:[1,0]
	v_cvt_pk_bf16_f32 v41, v86, v46
	ds_write_b16 v88, v41 offset:4352
	ds_write_b16_d16_hi v88, v41 offset:4480
	v_add_f32_e32 v42, v241, v233
	v_add_f32_e32 v43, v245, v237
	v_pk_mul_f32 v[44:45], v[50:51], v[46:47]
	s_nop 0
	v_pk_fma_f32 v[44:45], v[60:61], v[86:87], v[44:45] neg_lo:[0,0,1] neg_hi:[0,0,1]
	s_nop 0
	v_pk_add_f32 v[134:135], v[44:45], v[42:43]
	v_pk_mul_f32 v[44:45], v[50:51], v[86:87]
	v_pk_fma_f32 v[44:45], v[60:61], v[46:47], v[44:45]
	v_pk_add_f32 v[46:47], v[44:45], v[42:43] op_sel:[0,1] op_sel_hi:[1,0]
	v_cvt_pk_bf16_f32 v41, v134, v46
	ds_write_b16 v88, v41 offset:4624
	ds_write_b16_d16_hi v88, v41 offset:4752
	v_add_f32_e32 v42, v242, v234
	v_add_f32_e32 v43, v246, v238
	v_pk_mul_f32 v[44:45], v[50:51], v[46:47]
	s_nop 0
	v_pk_fma_f32 v[44:45], v[60:61], v[134:135], v[44:45] neg_lo:[0,0,1] neg_hi:[0,0,1]
	s_nop 0
	v_pk_add_f32 v[86:87], v[44:45], v[42:43]
	v_pk_mul_f32 v[44:45], v[50:51], v[134:135]
	v_pk_fma_f32 v[44:45], v[60:61], v[46:47], v[44:45]
	v_pk_add_f32 v[46:47], v[44:45], v[42:43] op_sel:[0,1] op_sel_hi:[1,0]
	v_cvt_pk_bf16_f32 v41, v86, v46
	ds_write_b16 v88, v41 offset:4896
	ds_write_b16_d16_hi v88, v41 offset:5024
	v_add_f32_e32 v42, v243, v235
	v_add_f32_e32 v43, v247, v239
	v_pk_mul_f32 v[44:45], v[50:51], v[46:47]
	s_nop 0
	v_pk_fma_f32 v[44:45], v[60:61], v[86:87], v[44:45] neg_lo:[0,0,1] neg_hi:[0,0,1]
	s_nop 0
	v_pk_add_f32 v[134:135], v[44:45], v[42:43]
	v_pk_mul_f32 v[44:45], v[50:51], v[86:87]
	v_pk_fma_f32 v[44:45], v[60:61], v[46:47], v[44:45]
	v_pk_add_f32 v[46:47], v[44:45], v[42:43] op_sel:[0,1] op_sel_hi:[1,0]
	v_cvt_pk_bf16_f32 v41, v134, v46
	ds_write_b16 v88, v41 offset:5168
	ds_write_b16_d16_hi v88, v41 offset:5296
	ds_read_b128 v[216:219], v248 offset:1280
	ds_read_b128 v[220:223], v248 offset:1296
	ds_read_b128 v[224:227], v248 offset:1312
	ds_read_b128 v[228:231], v248 offset:1328
	s_waitcnt lgkmcnt(0)
	v_mfma_f32_4x4x1_16b_f32 v[232:235], v216, v64, 0
	v_mfma_f32_4x4x1_16b_f32 v[236:239], v216, v65, 0
	v_mfma_f32_4x4x1_16b_f32 v[240:243], v217, v12, 0
	v_mfma_f32_4x4x1_16b_f32 v[244:247], v217, v13, 0
	v_mfma_f32_4x4x1_16b_f32 v[232:235], v218, v66, v[232:235]
	v_mfma_f32_4x4x1_16b_f32 v[236:239], v218, v67, v[236:239]
	v_mfma_f32_4x4x1_16b_f32 v[240:243], v219, v14, v[240:243]
	v_mfma_f32_4x4x1_16b_f32 v[244:247], v219, v15, v[244:247]
	v_mfma_f32_4x4x1_16b_f32 v[232:235], v220, v68, v[232:235]
	v_mfma_f32_4x4x1_16b_f32 v[236:239], v220, v69, v[236:239]
	v_mfma_f32_4x4x1_16b_f32 v[240:243], v221, v8, v[240:243]
	v_mfma_f32_4x4x1_16b_f32 v[244:247], v221, v9, v[244:247]
	v_mfma_f32_4x4x1_16b_f32 v[232:235], v222, v70, v[232:235]
	v_mfma_f32_4x4x1_16b_f32 v[236:239], v222, v71, v[236:239]
	v_mfma_f32_4x4x1_16b_f32 v[240:243], v223, v10, v[240:243]
	v_mfma_f32_4x4x1_16b_f32 v[244:247], v223, v11, v[244:247]
	v_mfma_f32_4x4x1_16b_f32 v[232:235], v224, v72, v[232:235]
	v_mfma_f32_4x4x1_16b_f32 v[236:239], v224, v73, v[236:239]
	v_mfma_f32_4x4x1_16b_f32 v[240:243], v225, v4, v[240:243]
	v_mfma_f32_4x4x1_16b_f32 v[244:247], v225, v5, v[244:247]
	v_mfma_f32_4x4x1_16b_f32 v[232:235], v226, v74, v[232:235]
	v_mfma_f32_4x4x1_16b_f32 v[236:239], v226, v75, v[236:239]
	v_mfma_f32_4x4x1_16b_f32 v[240:243], v227, v6, v[240:243]
	v_mfma_f32_4x4x1_16b_f32 v[244:247], v227, v7, v[244:247]
	v_mfma_f32_4x4x1_16b_f32 v[232:235], v228, v76, v[232:235]
; #define LAS __attribute__((address_space(3)))
; __device__ __forceinline__ unsigned f2bf(float f) { unsigned u = __builtin_bit_cast(unsigned, f); return (u + 0x7fffu + ((u >> 16) & 1u)) >> 16; }
; __device__ __forceinline__ void s5_phase(LAS unsigned char* lds, const unsigned char* ws, const bf16_t* proj, const float* c_re, const float* c_im, const float* dskip, bf16_t* z,
;                                          int vcu, int G, int wave, int lane) {
;     ...
;             for (int k = 0; k < 32; ++k) {
;                 f32x2 xa = (f32x2){0.f, 0.f}, xb = (f32x2){0.f, 0.f};
; #pragma unroll
;                 for (int q = 0; q < 4; ++q) { const f32x4 u4 = *(const LAS f32x4*)(Uc + k * 16 + 4 * q);
;                     xa = __builtin_elementwise_fma((f32x2){u4[0], u4[0]}, (f32x2){bbre[4 * q], bbim[4 * q]}, xa);
;                     xb = __builtin_elementwise_fma((f32x2){u4[1], u4[1]}, (f32x2){bbre[4 * q + 1], bbim[4 * q + 1]}, xb);
;                     xa = __builtin_elementwise_fma((f32x2){u4[2], u4[2]}, (f32x2){bbre[4 * q + 2], bbim[4 * q + 2]}, xa);
;                     xb = __builtin_elementwise_fma((f32x2){u4[3], u4[3]}, (f32x2){bbre[4 * q + 3], bbim[4 * q + 3]}, xb); }
;                 const f32x2 xx = xa + xb;
;                 const float nr = are * hre - aim * him + xx[0], ni = are * him + aim * hre + xx[1]; hre = nr; him = ni;
;                 Hc[k * 136 + n] = (bf16_t)f2bf(hre); Hc[k * 136 + 64 + n] = (bf16_t)f2bf(him);
	v_mfma_f32_4x4x1_16b_f32 v[236:239], v228, v77, v[236:239]
	v_mfma_f32_4x4x1_16b_f32 v[240:243], v229, v0, v[240:243]
	v_mfma_f32_4x4x1_16b_f32 v[244:247], v229, v1, v[244:247]
	v_mfma_f32_4x4x1_16b_f32 v[232:235], v230, v78, v[232:235]
	v_mfma_f32_4x4x1_16b_f32 v[236:239], v230, v79, v[236:239]
	v_mfma_f32_4x4x1_16b_f32 v[240:243], v231, v2, v[240:243]
	v_mfma_f32_4x4x1_16b_f32 v[244:247], v231, v3, v[244:247]
	s_nop 4
	v_add_f32_e32 v42, v240, v232
	v_add_f32_e32 v43, v244, v236
	v_pk_mul_f32 v[44:45], v[50:51], v[46:47]
	s_nop 0
	v_pk_fma_f32 v[44:45], v[60:61], v[134:135], v[44:45] neg_lo:[0,0,1] neg_hi:[0,0,1]
	s_nop 0
	v_pk_add_f32 v[86:87], v[44:45], v[42:43]
	v_pk_mul_f32 v[44:45], v[50:51], v[134:135]
	v_pk_fma_f32 v[44:45], v[60:61], v[46:47], v[44:45]
	v_pk_add_f32 v[46:47], v[44:45], v[42:43] op_sel:[0,1] op_sel_hi:[1,0]
	v_cvt_pk_bf16_f32 v41, v86, v46
	ds_write_b16 v88, v41 offset:5440
	ds_write_b16_d16_hi v88, v41 offset:5568
	v_add_f32_e32 v42, v241, v233
	v_add_f32_e32 v43, v245, v237
	v_pk_mul_f32 v[44:45], v[50:51], v[46:47]
	s_nop 0
	v_pk_fma_f32 v[44:45], v[60:61], v[86:87], v[44:45] neg_lo:[0,0,1] neg_hi:[0,0,1]
	s_nop 0
	v_pk_add_f32 v[134:135], v[44:45], v[42:43]
	v_pk_mul_f32 v[44:45], v[50:51], v[86:87]
	v_pk_fma_f32 v[44:45], v[60:61], v[46:47], v[44:45]
	v_pk_add_f32 v[46:47], v[44:45], v[42:43] op_sel:[0,1] op_sel_hi:[1,0]
	v_cvt_pk_bf16_f32 v41, v134, v46
	ds_write_b16 v88, v41 offset:5712
	ds_write_b16_d16_hi v88, v41 offset:5840
	v_add_f32_e32 v42, v242, v234
	v_add_f32_e32 v43, v246, v238
	v_pk_mul_f32 v[44:45], v[50:51], v[46:47]
	s_nop 0
	v_pk_fma_f32 v[44:45], v[60:61], v[134:135], v[44:45] neg_lo:[0,0,1] neg_hi:[0,0,1]
	s_nop 0
	v_pk_add_f32 v[86:87], v[44:45], v[42:43]
	v_pk_mul_f32 v[44:45], v[50:51], v[134:135]
	v_pk_fma_f32 v[44:45], v[60:61], v[46:47], v[44:45]
	v_pk_add_f32 v[46:47], v[44:45], v[42:43] op_sel:[0,1] op_sel_hi:[1,0]
	v_cvt_pk_bf16_f32 v41, v86, v46
	ds_write_b16 v88, v41 offset:5984
	ds_write_b16_d16_hi v88, v41 offset:6112
	v_add_f32_e32 v42, v243, v235
	v_add_f32_e32 v43, v247, v239
	v_pk_mul_f32 v[44:45], v[50:51], v[46:47]
	s_nop 0
	v_pk_fma_f32 v[44:45], v[60:61], v[86:87], v[44:45] neg_lo:[0,0,1] neg_hi:[0,0,1]
	s_nop 0
	v_pk_add_f32 v[134:135], v[44:45], v[42:43]
	v_pk_mul_f32 v[44:45], v[50:51], v[86:87]
	v_pk_fma_f32 v[44:45], v[60:61], v[46:47], v[44:45]
	v_pk_add_f32 v[46:47], v[44:45], v[42:43] op_sel:[0,1] op_sel_hi:[1,0]
	v_cvt_pk_bf16_f32 v41, v134, v46
	ds_write_b16 v88, v41 offset:6256
	ds_write_b16_d16_hi v88, v41 offset:6384
	ds_read_b128 v[216:219], v248 offset:1536
	ds_read_b128 v[220:223], v248 offset:1552
	ds_read_b128 v[224:227], v248 offset:1568
	ds_read_b128 v[228:231], v248 offset:1584
	s_waitcnt lgkmcnt(0)
	v_mfma_f32_4x4x1_16b_f32 v[232:235], v216, v64, 0
	v_mfma_f32_4x4x1_16b_f32 v[236:239], v216, v65, 0
	v_mfma_f32_4x4x1_16b_f32 v[240:243], v217, v12, 0
	v_mfma_f32_4x4x1_16b_f32 v[244:247], v217, v13, 0
	v_mfma_f32_4x4x1_16b_f32 v[232:235], v218, v66, v[232:235]
	v_mfma_f32_4x4x1_16b_f32 v[236:239], v218, v67, v[236:239]
	v_mfma_f32_4x4x1_16b_f32 v[240:243], v219, v14, v[240:243]
	v_mfma_f32_4x4x1_16b_f32 v[244:247], v219, v15, v[244:247]
	v_mfma_f32_4x4x1_16b_f32 v[232:235], v220, v68, v[232:235]
	v_mfma_f32_4x4x1_16b_f32 v[236:239], v220, v69, v[236:239]
	v_mfma_f32_4x4x1_16b_f32 v[240:243], v221, v8, v[240:243]
	v_mfma_f32_4x4x1_16b_f32 v[244:247], v221, v9, v[244:247]
	v_mfma_f32_4x4x1_16b_f32 v[232:235], v222, v70, v[232:235]
	v_mfma_f32_4x4x1_16b_f32 v[236:239], v222, v71, v[236:239]
	v_mfma_f32_4x4x1_16b_f32 v[240:243], v223, v10, v[240:243]
	v_mfma_f32_4x4x1_16b_f32 v[244:247], v223, v11, v[244:247]
	v_mfma_f32_4x4x1_16b_f32 v[232:235], v224, v72, v[232:235]
	v_mfma_f32_4x4x1_16b_f32 v[236:239], v224, v73, v[236:239]
	v_mfma_f32_4x4x1_16b_f32 v[240:243], v225, v4, v[240:243]
	v_mfma_f32_4x4x1_16b_f32 v[244:247], v225, v5, v[244:247]
	v_mfma_f32_4x4x1_16b_f32 v[232:235], v226, v74, v[232:235]
	v_mfma_f32_4x4x1_16b_f32 v[236:239], v226, v75, v[236:239]
	v_mfma_f32_4x4x1_16b_f32 v[240:243], v227, v6, v[240:243]
	v_mfma_f32_4x4x1_16b_f32 v[244:247], v227, v7, v[244:247]
	v_mfma_f32_4x4x1_16b_f32 v[232:235], v228, v76, v[232:235]
	v_mfma_f32_4x4x1_16b_f32 v[236:239], v228, v77, v[236:239]
	v_mfma_f32_4x4x1_16b_f32 v[240:243], v229, v0, v[240:243]
	v_mfma_f32_4x4x1_16b_f32 v[244:247], v229, v1, v[244:247]
	v_mfma_f32_4x4x1_16b_f32 v[232:235], v230, v78, v[232:235]
	v_mfma_f32_4x4x1_16b_f32 v[236:239], v230, v79, v[236:239]
	v_mfma_f32_4x4x1_16b_f32 v[240:243], v231, v2, v[240:243]
	v_mfma_f32_4x4x1_16b_f32 v[244:247], v231, v3, v[244:247]
	s_nop 4
	v_add_f32_e32 v42, v240, v232
	v_add_f32_e32 v43, v244, v236
	v_pk_mul_f32 v[44:45], v[50:51], v[46:47]
	s_nop 0
	v_pk_fma_f32 v[44:45], v[60:61], v[134:135], v[44:45] neg_lo:[0,0,1] neg_hi:[0,0,1]
	s_nop 0
	v_pk_add_f32 v[86:87], v[44:45], v[42:43]
	v_pk_mul_f32 v[44:45], v[50:51], v[134:135]
	v_pk_fma_f32 v[44:45], v[60:61], v[46:47], v[44:45]
	v_pk_add_f32 v[46:47], v[44:45], v[42:43] op_sel:[0,1] op_sel_hi:[1,0]
	v_cvt_pk_bf16_f32 v41, v86, v46
	ds_write_b16 v88, v41 offset:6528
	ds_write_b16_d16_hi v88, v41 offset:6656
	v_add_f32_e32 v42, v241, v233
	v_add_f32_e32 v43, v245, v237
	v_pk_mul_f32 v[44:45], v[50:51], v[46:47]
	s_nop 0
	v_pk_fma_f32 v[44:45], v[60:61], v[86:87], v[44:45] neg_lo:[0,0,1] neg_hi:[0,0,1]
	s_nop 0
	v_pk_add_f32 v[134:135], v[44:45], v[42:43]
	v_pk_mul_f32 v[44:45], v[50:51], v[86:87]
	v_pk_fma_f32 v[44:45], v[60:61], v[46:47], v[44:45]
	v_pk_add_f32 v[46:47], v[44:45], v[42:43] op_sel:[0,1] op_sel_hi:[1,0]
	v_cvt_pk_bf16_f32 v41, v134, v46
	ds_write_b16 v88, v41 offset:6800
	ds_write_b16_d16_hi v88, v41 offset:6928
	v_add_f32_e32 v42, v242, v234
	v_add_f32_e32 v43, v246, v238
	v_pk_mul_f32 v[44:45], v[50:51], v[46:47]
	s_nop 0
	v_pk_fma_f32 v[44:45], v[60:61], v[134:135], v[44:45] neg_lo:[0,0,1] neg_hi:[0,0,1]
	s_nop 0
	v_pk_add_f32 v[86:87], v[44:45], v[42:43]
	v_pk_mul_f32 v[44:45], v[50:51], v[134:135]
	v_pk_fma_f32 v[44:45], v[60:61], v[46:47], v[44:45]
	v_pk_add_f32 v[46:47], v[44:45], v[42:43] op_sel:[0,1] op_sel_hi:[1,0]
	v_cvt_pk_bf16_f32 v41, v86, v46
	ds_write_b16 v88, v41 offset:7072
	ds_write_b16_d16_hi v88, v41 offset:7200
	v_add_f32_e32 v42, v243, v235
	v_add_f32_e32 v43, v247, v239
	v_pk_mul_f32 v[44:45], v[50:51], v[46:47]
	s_nop 0
	v_pk_fma_f32 v[44:45], v[60:61], v[86:87], v[44:45] neg_lo:[0,0,1] neg_hi:[0,0,1]
	s_nop 0
	v_pk_add_f32 v[134:135], v[44:45], v[42:43]
	v_pk_mul_f32 v[44:45], v[50:51], v[86:87]
	v_pk_fma_f32 v[44:45], v[60:61], v[46:47], v[44:45]
	v_pk_add_f32 v[46:47], v[44:45], v[42:43] op_sel:[0,1] op_sel_hi:[1,0]
	v_cvt_pk_bf16_f32 v41, v134, v46
	ds_write_b16 v88, v41 offset:7344
	ds_write_b16_d16_hi v88, v41 offset:7472
	ds_read_b128 v[216:219], v248 offset:1792
	ds_read_b128 v[220:223], v248 offset:1808
	ds_read_b128 v[224:227], v248 offset:1824
	ds_read_b128 v[228:231], v248 offset:1840
	s_waitcnt lgkmcnt(0)
; #define LAS __attribute__((address_space(3)))
; __device__ __forceinline__ unsigned f2bf(float f) { unsigned u = __builtin_bit_cast(unsigned, f); return (u + 0x7fffu + ((u >> 16) & 1u)) >> 16; }
; __device__ __forceinline__ void s5_phase(LAS unsigned char* lds, const unsigned char* ws, const bf16_t* proj, const float* c_re, const float* c_im, const float* dskip, bf16_t* z,
;                                          int vcu, int G, int wave, int lane) {
;     ...
;             for (int k = 0; k < 32; ++k) {
;                 f32x2 xa = (f32x2){0.f, 0.f}, xb = (f32x2){0.f, 0.f};
; #pragma unroll
;                 for (int q = 0; q < 4; ++q) { const f32x4 u4 = *(const LAS f32x4*)(Uc + k * 16 + 4 * q);
;                     xa = __builtin_elementwise_fma((f32x2){u4[0], u4[0]}, (f32x2){bbre[4 * q], bbim[4 * q]}, xa);
;                     xb = __builtin_elementwise_fma((f32x2){u4[1], u4[1]}, (f32x2){bbre[4 * q + 1], bbim[4 * q + 1]}, xb);
;                     xa = __builtin_elementwise_fma((f32x2){u4[2], u4[2]}, (f32x2){bbre[4 * q + 2], bbim[4 * q + 2]}, xa);
;                     xb = __builtin_elementwise_fma((f32x2){u4[3], u4[3]}, (f32x2){bbre[4 * q + 3], bbim[4 * q + 3]}, xb); }
;                 const f32x2 xx = xa + xb;
;                 const float nr = are * hre - aim * him + xx[0], ni = are * him + aim * hre + xx[1]; hre = nr; him = ni;
;                 Hc[k * 136 + n] = (bf16_t)f2bf(hre); Hc[k * 136 + 64 + n] = (bf16_t)f2bf(him);
;             }
; #pragma unroll
;             for (int sb = 0; sb < 2; ++sb) {
;                 f32x4 y = (f32x4){0.f, 0.f, 0.f, 0.f};
; #pragma unroll
;                 for (int ks = 0; ks < 4; ++ks) { const bf16x8 hf = *(const LAS bf16x8*)(Hc + (16 * sb + fr) * 136 + 32 * ks + 8 * fq); y = __builtin_amdgcn_mfma_f32_16x16x32_bf16(hf, cf[ks], y, 0, 0, 0); }
	v_mfma_f32_4x4x1_16b_f32 v[232:235], v216, v64, 0
	v_mfma_f32_4x4x1_16b_f32 v[236:239], v216, v65, 0
	v_mfma_f32_4x4x1_16b_f32 v[240:243], v217, v12, 0
	v_mfma_f32_4x4x1_16b_f32 v[244:247], v217, v13, 0
	v_mfma_f32_4x4x1_16b_f32 v[232:235], v218, v66, v[232:235]
	v_mfma_f32_4x4x1_16b_f32 v[236:239], v218, v67, v[236:239]
	v_mfma_f32_4x4x1_16b_f32 v[240:243], v219, v14, v[240:243]
	v_mfma_f32_4x4x1_16b_f32 v[244:247], v219, v15, v[244:247]
	v_mfma_f32_4x4x1_16b_f32 v[232:235], v220, v68, v[232:235]
	v_mfma_f32_4x4x1_16b_f32 v[236:239], v220, v69, v[236:239]
	v_mfma_f32_4x4x1_16b_f32 v[240:243], v221, v8, v[240:243]
	v_mfma_f32_4x4x1_16b_f32 v[244:247], v221, v9, v[244:247]
	v_mfma_f32_4x4x1_16b_f32 v[232:235], v222, v70, v[232:235]
	v_mfma_f32_4x4x1_16b_f32 v[236:239], v222, v71, v[236:239]
	v_mfma_f32_4x4x1_16b_f32 v[240:243], v223, v10, v[240:243]
	v_mfma_f32_4x4x1_16b_f32 v[244:247], v223, v11, v[244:247]
	v_mfma_f32_4x4x1_16b_f32 v[232:235], v224, v72, v[232:235]
	v_mfma_f32_4x4x1_16b_f32 v[236:239], v224, v73, v[236:239]
	v_mfma_f32_4x4x1_16b_f32 v[240:243], v225, v4, v[240:243]
	v_mfma_f32_4x4x1_16b_f32 v[244:247], v225, v5, v[244:247]
	v_mfma_f32_4x4x1_16b_f32 v[232:235], v226, v74, v[232:235]
	v_mfma_f32_4x4x1_16b_f32 v[236:239], v226, v75, v[236:239]
	v_mfma_f32_4x4x1_16b_f32 v[240:243], v227, v6, v[240:243]
	v_mfma_f32_4x4x1_16b_f32 v[244:247], v227, v7, v[244:247]
	v_mfma_f32_4x4x1_16b_f32 v[232:235], v228, v76, v[232:235]
	v_mfma_f32_4x4x1_16b_f32 v[236:239], v228, v77, v[236:239]
	v_mfma_f32_4x4x1_16b_f32 v[240:243], v229, v0, v[240:243]
	v_mfma_f32_4x4x1_16b_f32 v[244:247], v229, v1, v[244:247]
	v_mfma_f32_4x4x1_16b_f32 v[232:235], v230, v78, v[232:235]
	v_mfma_f32_4x4x1_16b_f32 v[236:239], v230, v79, v[236:239]
	v_mfma_f32_4x4x1_16b_f32 v[240:243], v231, v2, v[240:243]
	v_mfma_f32_4x4x1_16b_f32 v[244:247], v231, v3, v[244:247]
	s_nop 4
	v_add_f32_e32 v42, v240, v232
	v_add_f32_e32 v43, v244, v236
	v_pk_mul_f32 v[44:45], v[50:51], v[46:47]
	s_nop 0
	v_pk_fma_f32 v[44:45], v[60:61], v[134:135], v[44:45] neg_lo:[0,0,1] neg_hi:[0,0,1]
	s_nop 0
	v_pk_add_f32 v[86:87], v[44:45], v[42:43]
	v_pk_mul_f32 v[44:45], v[50:51], v[134:135]
	v_pk_fma_f32 v[44:45], v[60:61], v[46:47], v[44:45]
	v_pk_add_f32 v[46:47], v[44:45], v[42:43] op_sel:[0,1] op_sel_hi:[1,0]
	v_cvt_pk_bf16_f32 v41, v86, v46
	ds_write_b16 v88, v41 offset:7616
	ds_write_b16_d16_hi v88, v41 offset:7744
	v_add_f32_e32 v42, v241, v233
	v_add_f32_e32 v43, v245, v237
	v_pk_mul_f32 v[44:45], v[50:51], v[46:47]
	s_nop 0
	v_pk_fma_f32 v[44:45], v[60:61], v[86:87], v[44:45] neg_lo:[0,0,1] neg_hi:[0,0,1]
	s_nop 0
	v_pk_add_f32 v[134:135], v[44:45], v[42:43]
	v_pk_mul_f32 v[44:45], v[50:51], v[86:87]
	v_pk_fma_f32 v[44:45], v[60:61], v[46:47], v[44:45]
	v_pk_add_f32 v[46:47], v[44:45], v[42:43] op_sel:[0,1] op_sel_hi:[1,0]
	v_cvt_pk_bf16_f32 v41, v134, v46
	ds_write_b16 v88, v41 offset:7888
	ds_write_b16_d16_hi v88, v41 offset:8016
	v_add_f32_e32 v42, v242, v234
	v_add_f32_e32 v43, v246, v238
	v_pk_mul_f32 v[44:45], v[50:51], v[46:47]
	s_nop 0
	v_pk_fma_f32 v[44:45], v[60:61], v[134:135], v[44:45] neg_lo:[0,0,1] neg_hi:[0,0,1]
	s_nop 0
	v_pk_add_f32 v[86:87], v[44:45], v[42:43]
	v_pk_mul_f32 v[44:45], v[50:51], v[134:135]
	v_pk_fma_f32 v[44:45], v[60:61], v[46:47], v[44:45]
	v_pk_add_f32 v[46:47], v[44:45], v[42:43] op_sel:[0,1] op_sel_hi:[1,0]
	v_cvt_pk_bf16_f32 v41, v86, v46
	ds_write_b16 v88, v41 offset:8160
	ds_write_b16_d16_hi v88, v41 offset:8288
	v_add_f32_e32 v40, v243, v235
	v_add_f32_e32 v41, v247, v239
	v_pk_mul_f32 v[42:43], v[80:81], v[46:47] op_sel_hi:[1,0]
	v_lshl_add_u64 v[130:131], v[82:83], 0, s[26:27]
	v_pk_fma_f32 v[44:45], v[60:61], v[86:87], v[42:43] neg_lo:[0,0,1] neg_hi:[0,0,1]
	v_pk_fma_f32 v[42:43], v[60:61], v[86:87], v[42:43] op_sel_hi:[1,0,1]
	s_nop 0
	v_mov_b32_e32 v45, v43
	v_pk_add_f32 v[86:87], v[44:45], v[40:41]
	s_nop 0
	v_cvt_pk_bf16_f32 v40, v86, v87
	ds_write_b16 v88, v40 offset:8432
	ds_write_b16_d16_hi v88, v40 offset:8560
	ds_read_b128 v[40:43], v102
	ds_read_b128 v[44:47], v102 offset:64
	s_waitcnt lgkmcnt(1)
	v_mfma_f32_16x16x32_bf16 v[40:43], v[40:43], v[16:19], 0
	ds_read_b128 v[122:125], v102 offset:128
	ds_read_b128 v[126:129], v102 offset:4544
	s_waitcnt lgkmcnt(2)
	v_mfma_f32_16x16x32_bf16 v[40:43], v[44:47], v[20:23], v[40:43]
	ds_read_b128 v[44:47], v102 offset:192
	s_waitcnt lgkmcnt(2)
	v_mfma_f32_16x16x32_bf16 v[40:43], v[122:125], v[24:27], v[40:43]
	ds_read_b128 v[122:125], v102 offset:4480
	s_waitcnt lgkmcnt(1)
; #define LAS __attribute__((address_space(3)))
; __device__ __forceinline__ unsigned f2bf(float f) { unsigned u = __builtin_bit_cast(unsigned, f); return (u + 0x7fffu + ((u >> 16) & 1u)) >> 16; }
; __device__ __forceinline__ float gelu_tanh_f(float y) { return y * fast_sigmoid(1.5957691216057308f * (y + 0.044715f * y * y * y)); }
; __device__ __forceinline__ void s5_phase(LAS unsigned char* lds, const unsigned char* ws, const bf16_t* proj, const float* c_re, const float* c_im, const float* dskip, bf16_t* z,
;                                          int vcu, int G, int wave, int lane) {
;     ...
; #pragma unroll
;             for (int sb = 0; sb < 2; ++sb) {
;                 f32x4 y = (f32x4){0.f, 0.f, 0.f, 0.f};
; #pragma unroll
;                 for (int ks = 0; ks < 4; ++ks) { const bf16x8 hf = *(const LAS bf16x8*)(Hc + (16 * sb + fr) * 136 + 32 * ks + 8 * fq); y = __builtin_amdgcn_mfma_f32_16x16x32_bf16(hf, cf[ks], y, 0, 0, 0); }
; #pragma unroll
;                 for (int i = 0; i < 4; ++i) { const size_t row = row0 + 16 * sb + 4 * fq + i;
;                     const float yy = y[i] + dsk * bf2f(uu[sb][i]);
;                     z[row * 1024 + g * 16 + fr] = (bf16_t)f2bf(gelu_tanh_f(yy)); }
;             }
;             ua = ua_n; ub = ub_n;
; #pragma unroll
;             for (int sb = 0; sb < 2; ++sb)
; #pragma unroll
;                 for (int i = 0; i < 4; ++i) uu[sb][i] = uu_n[sb][i];
	v_mfma_f32_16x16x32_bf16 v[40:43], v[44:47], v[28:31], v[40:43]
	v_lshlrev_b32_e32 v44, 16, v120
	s_nop 6
	v_fma_f32 v40, v104, v44, v40
	v_mul_f32_e32 v44, 0x3d372713, v40
	v_mul_f32_e32 v44, v40, v44
	v_fma_f32 v44, v40, v44, v40
	v_mul_f32_e32 v44, 0x3fcc422a, v44
	v_mul_f32_e32 v44, 0xbfb8aa3b, v44
	v_exp_f32_e32 v44, v44
	s_nop 0
	v_add_f32_e32 v44, 1.0, v44
	v_rcp_f32_e32 v44, v44
	s_nop 0
	v_mul_f32_e32 v40, v40, v44
	v_bfe_u32 v44, v40, 16, 1
	v_add3_u32 v46, v40, v44, s29
	v_lshlrev_b32_e32 v40, 16, v119
	v_fma_f32 v47, v104, v40, v41
	v_mul_f32_e32 v40, 0x3d372713, v47
	v_mul_f32_e32 v40, v47, v40
	v_fma_f32 v40, v47, v40, v47
	v_mul_f32_e32 v40, 0x3fcc422a, v40
	v_mul_f32_e32 v40, 0xbfb8aa3b, v40
	v_lshl_add_u64 v[44:45], v[84:85], 0, s[26:27]
	v_exp_f32_e32 v119, v40
	v_add_co_u32_e64 v40, s[0:1], s31, v44
	s_add_u32 s26, s26, 0x10000
	s_nop 0
	v_addc_co_u32_e64 v41, s[0:1], 0, v45, s[0:1]
	v_add_co_u32_e64 v132, s[0:1], s33, v44
	v_add_f32_e32 v119, 1.0, v119
	s_nop 0
	v_addc_co_u32_e64 v133, s[0:1], 0, v45, s[0:1]
	v_rcp_f32_e32 v119, v119
	global_store_short_d16_hi v[132:133], v46, off offset:-4096
	v_lshlrev_b32_e32 v46, 16, v118
	v_fma_f32 v42, v104, v46, v42
	v_mul_f32_e32 v46, 0x3d372713, v42
	v_mul_f32_e32 v46, v42, v46
	v_mul_f32_e32 v44, v47, v119
	v_fma_f32 v46, v42, v46, v42
	v_bfe_u32 v45, v44, 16, 1
	v_mul_f32_e32 v46, 0x3fcc422a, v46
	v_mul_f32_e32 v46, 0xbfb8aa3b, v46
	v_add3_u32 v44, v44, v45, s29
	v_exp_f32_e32 v118, v46
	global_store_short_d16_hi v[40:41], v44, off offset:2048
	ds_read_b128 v[44:47], v102 offset:4352
	v_lshlrev_b32_e32 v41, 16, v109
	v_add_f32_e32 v40, 1.0, v118
	ds_read_b128 v[118:121], v102 offset:4416
	s_waitcnt lgkmcnt(1)
	v_mfma_f32_16x16x32_bf16 v[44:47], v[44:47], v[16:19], 0
	v_fmac_f32_e32 v43, v104, v41
	v_mul_f32_e32 v41, 0x3d372713, v43
	v_mul_f32_e32 v41, v43, v41
	s_waitcnt lgkmcnt(0)
	v_mfma_f32_16x16x32_bf16 v[44:47], v[118:121], v[20:23], v[44:47]
	v_fma_f32 v41, v43, v41, v43
	v_mul_f32_e32 v41, 0x3fcc422a, v41
	v_mul_f32_e32 v41, 0xbfb8aa3b, v41
	v_mfma_f32_16x16x32_bf16 v[44:47], v[122:125], v[24:27], v[44:47]
	v_exp_f32_e32 v41, v41
	v_rcp_f32_e32 v40, v40
	s_addc_u32 s27, s27, 0
	v_mfma_f32_16x16x32_bf16 v[44:47], v[126:129], v[28:31], v[44:47]
	v_add_f32_e32 v41, 1.0, v41
	v_rcp_f32_e32 v41, v41
	v_mul_f32_e32 v40, v42, v40
	v_bfe_u32 v42, v40, 16, 1
	v_add3_u32 v40, v40, v42, s29
	s_nop 2
	v_fma_f32 v44, v104, v108, v44
	v_mul_f32_e32 v108, 0x3d372713, v44
	v_mul_f32_e32 v108, v44, v108
	v_fma_f32 v108, v44, v108, v44
	v_mul_f32_e32 v108, 0x3fcc422a, v108
	v_mul_f32_e32 v108, 0xbfb8aa3b, v108
	v_exp_f32_e32 v108, v108
	global_store_short_d16_hi v[132:133], v40, off
	v_mul_f32_e32 v40, v43, v41
	v_bfe_u32 v42, v40, 16, 1
	v_add_f32_e32 v41, 1.0, v108
	v_rcp_f32_e32 v41, v41
	v_add3_u32 v40, v40, v42, s29
	global_store_short_d16_hi v[132:133], v40, off offset:2048
	s_add_i32 s34, s34, 0x28000
	v_mul_f32_e32 v40, v44, v41
	s_waitcnt vmcnt(16)
	v_lshlrev_b32_e32 v41, 16, v107
	v_fma_f32 v42, v104, v41, v45
	v_mul_f32_e32 v41, 0x3d372713, v42
	v_mul_f32_e32 v41, v42, v41
	v_fma_f32 v41, v42, v41, v42
	v_mul_f32_e32 v41, 0x3fcc422a, v41
	v_mul_f32_e32 v41, 0xbfb8aa3b, v41
	v_exp_f32_e32 v41, v41
	v_bfe_u32 v43, v40, 16, 1
	v_add3_u32 v43, v40, v43, s29
	v_or_b32_e32 v40, 0x8000, v130
	v_add_f32_e32 v41, 1.0, v41
	v_rcp_f32_e32 v44, v41
	v_mov_b32_e32 v41, v131
	v_lshl_add_u64 v[40:41], v[62:63], 0, v[40:41]
	global_store_short_d16_hi v[40:41], v43, off
	s_waitcnt vmcnt(16)
	v_lshlrev_b32_e32 v41, 16, v106
	v_mul_f32_e32 v40, v42, v44
	v_fma_f32 v42, v104, v41, v46
	v_mul_f32_e32 v41, 0x3d372713, v42
	v_mul_f32_e32 v41, v42, v41
	v_fma_f32 v41, v42, v41, v42
	v_mul_f32_e32 v41, 0x3fcc422a, v41
	v_mul_f32_e32 v41, 0xbfb8aa3b, v41
	v_exp_f32_e32 v41, v41
	v_bfe_u32 v43, v40, 16, 1
	v_add3_u32 v43, v40, v43, s29
	v_or_b32_e32 v40, 0x8800, v130
	v_add_f32_e32 v41, 1.0, v41
	v_rcp_f32_e32 v44, v41
	v_mov_b32_e32 v41, v131
	v_lshl_add_u64 v[40:41], v[62:63], 0, v[40:41]
	global_store_short_d16_hi v[40:41], v43, off
	s_waitcnt vmcnt(16)
	v_lshlrev_b32_e32 v41, 16, v105
	v_fmac_f32_e32 v47, v104, v41
	v_mul_f32_e32 v41, 0x3d372713, v47
	v_mul_f32_e32 v41, v47, v41
	v_fma_f32 v41, v47, v41, v47
	v_mul_f32_e32 v41, 0x3fcc422a, v41
	v_mul_f32_e32 v41, 0xbfb8aa3b, v41
	v_exp_f32_e32 v41, v41
	v_mul_f32_e32 v40, v42, v44
	v_bfe_u32 v42, v40, 16, 1
	v_add3_u32 v42, v40, v42, s29
	v_add_f32_e32 v41, 1.0, v41
	v_rcp_f32_e32 v43, v41
	v_or_b32_e32 v40, 0x9000, v130
	v_mov_b32_e32 v41, v131
	v_lshl_add_u64 v[40:41], v[62:63], 0, v[40:41]
	global_store_short_d16_hi v[40:41], v42, off
	v_mul_f32_e32 v40, v47, v43
	v_bfe_u32 v41, v40, 16, 1
	v_or_b32_e32 v130, 0x9800, v130
	v_add3_u32 v42, v40, v41, s29
	v_lshl_add_u64 v[40:41], v[62:63], 0, v[130:131]
	global_store_short_d16_hi v[40:41], v42, off
	s_waitcnt vmcnt(16)
	v_mov_b64_e32 v[46:47], v[38:39]
	v_mov_b64_e32 v[42:43], v[34:35]
	s_cmp_eq_u32 s26, 0x400000
	s_waitcnt vmcnt(13)
	v_mov_b32_e32 v118, v117
	v_mov_b32_e32 v119, v111
	v_mov_b32_e32 v120, v110
	s_waitcnt vmcnt(12)
	v_mov_b32_e32 v109, v112
	s_waitcnt vmcnt(11)
	v_mov_b32_e32 v108, v113
	s_waitcnt vmcnt(10)
	v_mov_b32_e32 v107, v114
	s_waitcnt vmcnt(9)
	v_mov_b32_e32 v106, v115
	s_waitcnt vmcnt(8)
	v_mov_b32_e32 v105, v116
	v_mov_b64_e32 v[44:45], v[36:37]
	v_mov_b64_e32 v[40:41], v[32:33]
	s_cbranch_scc1 .LBB0_384
